# FFN-up tiles ordered in groups of 4 M-tiles (4x8 tile footprint per XCD round); x->bf16 prep loop unrolled x4
# speedup vs baseline: 1.0197x; 1.0033x over previous
; __device__ __forceinline__ unsigned cvt_pk_bf16(float lo, float hi) { const f32x2_t v = {lo, hi}; const bf16x2_t b = __builtin_convertvector(v, bf16x2_t); return __builtin_bit_cast(unsigned, b); }
; __device__ __forceinline__ void cvt_rows_bf16(const float* src, bf16_t* dst, size_t n8, size_t gtid, size_t nthr) {
;     for (size_t i = gtid; i < n8; i += nthr) { const f32x4 a = *(const f32x4*)(src + i * 8), b = *(const f32x4*)(src + i * 8 + 4);
;         u32x4 w; w.x = cvt_pk_bf16(a[0], a[1]); w.y = cvt_pk_bf16(a[2], a[3]); w.z = cvt_pk_bf16(b[0], b[1]); w.w = cvt_pk_bf16(b[2], b[3]); *(u32x4*)(dst + i * 8) = w; }
; }
; __global__ void __launch_bounds__(512) mega_fwd(Params p) {
;     ...
;         cvt_rows_bf16(p.in[I_X], xb, (size_t)NTOK * DM / 8, gtid, nthr);
.LBB0_46:
	s_mov_b32 s59, 0
	s_lshl_b64 s[0:1], s[58:59], 9
	v_writelane_b32 v252, s0, 32
	v_ashrrev_i32_e32 v3, 31, v2
	s_mov_b64 s[6:7], 0x800000
	v_writelane_b32 v252, s1, 33
	v_lshl_add_u64 v[4:5], s[0:1], 0, v[2:3]
	v_readlane_b32 s0, v252, 0
	v_readlane_b32 s1, v252, 1
	s_ashr_i32 s1, s0, 31
	s_mov_b64 s[20:21], s[58:59]
	s_lshl_b64 s[18:19], s[0:1], 9
	v_cmp_gt_u64_e32 vcc, s[6:7], v[4:5]
	v_lshlrev_b64 v[6:7], 5, v[2:3]
	s_and_saveexec_b64 s[6:7], vcc
	s_cbranch_execz .LBB0_49
	s_lshl_b64 s[8:9], s[20:21], 14
	s_add_u32 s8, s40, s8
	s_addc_u32 s9, s41, s9
	v_lshl_add_u64 v[8:9], s[8:9], 0, v[6:7]
	s_lshl_b64 s[8:9], s[0:1], 14
	s_lshl_b64 s[10:11], s[20:21], 13
	s_add_u32 s10, s74, s10
	s_addc_u32 s11, s75, s11
	v_lshl_add_u64 v[10:11], v[2:3], 4, s[10:11]
	s_mov_b64 s[10:11], 0xc200000
	v_lshl_add_u64 v[8:9], v[8:9], 0, 16
	v_lshl_add_u64 v[10:11], v[10:11], 0, s[10:11]
	s_lshl_b64 s[10:11], s[0:1], 13
	s_mov_b64 s[12:13], 0
	s_mov_b64 s[14:15], 0x7fffff
	v_mov_b64_e32 v[12:13], v[4:5]
	s_cmp_lg_u32 s0, 0x100
	s_cbranch_scc1 .LBB0_48
.Lcvt4_loop:
	global_load_dwordx4 v[14:17], v[8:9], off offset:-16
	global_load_dwordx4 v[18:21], v[8:9], off
	v_lshl_add_u64 v[22:23], v[8:9], 0, s[8:9]
	global_load_dwordx4 v[26:29], v[22:23], off offset:-16
	global_load_dwordx4 v[30:33], v[22:23], off
	v_lshl_add_u64 v[22:23], v[22:23], 0, s[8:9]
	global_load_dwordx4 v[34:37], v[22:23], off offset:-16
	global_load_dwordx4 v[38:41], v[22:23], off
	v_lshl_add_u64 v[22:23], v[22:23], 0, s[8:9]
	global_load_dwordx4 v[42:45], v[22:23], off offset:-16
	global_load_dwordx4 v[46:49], v[22:23], off
	v_lshl_add_u64 v[8:9], v[22:23], 0, s[8:9]
	v_lshl_add_u64 v[12:13], v[12:13], 0, s[18:19]
	v_lshl_add_u64 v[12:13], v[12:13], 0, s[18:19]
	v_lshl_add_u64 v[12:13], v[12:13], 0, s[18:19]
	v_lshl_add_u64 v[12:13], v[12:13], 0, s[18:19]
	v_cmp_lt_u64_e32 vcc, s[14:15], v[12:13]
	s_or_b64 s[12:13], vcc, s[12:13]
	s_waitcnt vmcnt(6)
	v_cvt_pk_bf16_f32 v14, v14, v15
	v_cvt_pk_bf16_f32 v15, v16, v17
	v_cvt_pk_bf16_f32 v16, v18, v19
	v_cvt_pk_bf16_f32 v17, v20, v21
	global_store_dwordx4 v[10:11], v[14:17], off
	v_lshl_add_u64 v[10:11], v[10:11], 0, s[10:11]
	s_waitcnt vmcnt(5)
	v_cvt_pk_bf16_f32 v26, v26, v27
	v_cvt_pk_bf16_f32 v27, v28, v29
	v_cvt_pk_bf16_f32 v28, v30, v31
	v_cvt_pk_bf16_f32 v29, v32, v33
	global_store_dwordx4 v[10:11], v[26:29], off
	v_lshl_add_u64 v[10:11], v[10:11], 0, s[10:11]
	s_waitcnt vmcnt(4)
	v_cvt_pk_bf16_f32 v34, v34, v35
	v_cvt_pk_bf16_f32 v35, v36, v37
	v_cvt_pk_bf16_f32 v36, v38, v39
	v_cvt_pk_bf16_f32 v37, v40, v41
	global_store_dwordx4 v[10:11], v[34:37], off
	v_lshl_add_u64 v[10:11], v[10:11], 0, s[10:11]
	s_waitcnt vmcnt(3)
	v_cvt_pk_bf16_f32 v42, v42, v43
	v_cvt_pk_bf16_f32 v43, v44, v45
	v_cvt_pk_bf16_f32 v44, v46, v47
	v_cvt_pk_bf16_f32 v45, v48, v49
	global_store_dwordx4 v[10:11], v[42:45], off
	v_lshl_add_u64 v[10:11], v[10:11], 0, s[10:11]
	s_andn2_b64 exec, exec, s[12:13]
	s_cbranch_execnz .Lcvt4_loop
	s_branch .LBB0_49

; __device__ __forceinline__ bool order_next(int i, int nM, int nN, int& pm, int& pn) {
;     const int G = gridDim.x, c = blockIdx.x, nwg = nM * nN;
;     int idx;
;     if ((G & 7) == 0) { const int xcd = c & 7, slot = c >> 3, per = G >> 3, q = (nwg + 7) >> 3; const int j = i * per + slot; if (j >= q) return false; idx = xcd * q + j; if (idx >= nwg) return false; }
;     else { idx = i * G + c; if (idx >= nwg) return false; }
;     const int nig = 2 * nN, gid = idx / nig, fm = gid * 2, gsz = (nM - fm) < 2 ? (nM - fm) : 2, r = idx % nig;
;     pm = fm + r % gsz; pn = r / gsz; return true;
;     __device__ __forceinline__ bool next(int i, Unit& u) const { int pm, pn; if (!order_next(i, nM, nN, pm, pn)) return false; u.pm = pm; u.pn = pn; u.pa = A + (size_t)pm * astep; u.pb = B + (size_t)pn * bstep; return true; }
.LBB0_663:
	s_andn2_b64 vcc, exec, s[0:1]
	s_mov_b64 s[2:3], 0
	s_cbranch_vccnz .LBB0_665
	s_mul_hi_i32 s0, s5, 0x2e8ba2e9
	s_lshr_b32 s1, s0, 31
	s_ashr_i32 s0, s0, 5
	s_add_i32 s0, s0, s1
	s_lshl_b32 s1, s0, 2
	s_mulk_i32 s0, 0xb0
	s_sub_i32 s0, s5, s0
	s_lshr_b32 s3, s0, 2
	s_and_b32 s0, s0, 3
	s_add_i32 s16, s1, s0
	s_mov_b32 s18, s3
	s_mov_b64 s[2:3], -1

; __device__ __forceinline__ bool order_next(int i, int nM, int nN, int& pm, int& pn) {
;     const int G = gridDim.x, c = blockIdx.x, nwg = nM * nN;
;     int idx;
;     if ((G & 7) == 0) { const int xcd = c & 7, slot = c >> 3, per = G >> 3, q = (nwg + 7) >> 3; const int j = i * per + slot; if (j >= q) return false; idx = xcd * q + j; if (idx >= nwg) return false; }
;     else { idx = i * G + c; if (idx >= nwg) return false; }
;     const int nig = 2 * nN, gid = idx / nig, fm = gid * 2, gsz = (nM - fm) < 2 ? (nM - fm) : 2, r = idx % nig;
;     pm = fm + r % gsz; pn = r / gsz; return true;
;     __device__ __forceinline__ bool next(int i, Unit& u) const { int pm, pn; if (!order_next(i, nM, nN, pm, pn)) return false; u.pm = pm; u.pn = pn; u.pa = A + (size_t)pm * astep; u.pb = B + (size_t)pn * bstep; return true; }
.LBB0_676:
	s_andn2_b64 vcc, exec, s[8:9]
	s_mov_b64 s[8:9], 0
	s_cbranch_vccnz .LBB0_678
	s_mul_hi_i32 s8, s17, 0x2e8ba2e9
	s_lshr_b32 s9, s8, 31
	s_ashr_i32 s8, s8, 5
	s_add_i32 s8, s8, s9
	s_lshl_b32 s9, s8, 2
	s_mulk_i32 s8, 0xb0
	s_sub_i32 s8, s17, s8
	s_lshr_b32 s11, s8, 2
	s_and_b32 s8, s8, 3
	s_add_i32 s94, s9, s8
	s_mov_b32 s60, s11
	s_mov_b64 s[8:9], -1
